# LN1 and ln0 row loops: modulation column loads hoisted and issued together instead of four serial load-wait pairs
# baseline (speedup 1.0000x reference)
.LBB0_33:
	v_readlane_b32 s7, v241, 20
	v_readlane_b32 s8, v243, 5
	v_readlane_b32 s14, v243, 11
	v_add_u32_e32 v52, s7, v42
	v_add_u32_e32 v35, 0xfffff000, v52
	v_lshrrev_b32_e32 v35, 10, v35
	s_movk_i32 s7, 0xfff
	v_add_u32_e32 v35, 1, v35
	v_cmp_lt_i32_e32 vcc, s7, v52
	v_readlane_b32 s15, v243, 12
	v_readlane_b32 s9, v243, 6
	v_cndmask_b32_e32 v35, 0, v35, vcc
	v_mov_b64_e32 v[44:45], s[14:15]
	v_mad_u64_u32 v[44:45], s[8:9], v35, s33, v[44:45]
	s_mov_b64 s[8:9], 0x1000
	s_nop 0
	v_lshl_add_u64 v[46:47], v[44:45], 0, s[8:9]
	v_ashrrev_i32_e32 v53, 31, v52
	v_lshl_add_u64 v[54:55], v[44:45], 0, v[128:129]
	v_lshl_add_u64 v[48:49], v[46:47], 0, v[128:129]
	v_mov_b32_e32 v35, v129
	v_mov_b32_e32 v37, v129
	v_mov_b32_e32 v39, v129
	v_lshlrev_b64 v[44:45], 12, v[52:53]
	v_lshl_add_u64 v[56:57], v[46:47], 0, v[34:35]
	v_lshl_add_u64 v[58:59], v[46:47], 0, v[36:37]
	v_lshl_add_u64 v[60:61], v[46:47], 0, v[38:39]
	v_lshl_add_u64 v[62:63], v[32:33], 0, v[44:45]
	global_load_dwordx4 v[44:47], v[54:55], off
	s_nop 0
	global_load_dwordx4 v[48:51], v[48:49], off
	global_load_dwordx4 v[68:71], v[54:55], off offset:1024
	global_load_dwordx4 v[72:75], v[56:57], off
	global_load_dwordx4 v[76:79], v[54:55], off offset:2048
	global_load_dwordx4 v[80:83], v[58:59], off
	global_load_dwordx4 v[84:87], v[54:55], off offset:3072
	global_load_dwordx4 v[88:91], v[60:61], off
	v_readlane_b32 s7, v240, 54
	s_and_b64 vcc, exec, s[4:5]
	v_readlane_b32 s10, v243, 7
	v_add_u32_e32 v42, s7, v42
	v_readlane_b32 s11, v243, 8
	v_readlane_b32 s12, v243, 9
	v_readlane_b32 s13, v243, 10
	v_readlane_b32 s16, v243, 13
	v_readlane_b32 s17, v243, 14
	v_readlane_b32 s18, v243, 15
	v_readlane_b32 s19, v243, 16
	v_readlane_b32 s20, v243, 17
	v_readlane_b32 s21, v243, 18
	v_readlane_b32 s22, v243, 19
	v_readlane_b32 s23, v243, 20
	s_waitcnt vmcnt(0)
	v_pk_add_f32 v[48:49], v[48:49], 1.0 op_sel_hi:[1,0]
	s_nop 0
	v_pk_fma_f32 v[44:45], v[28:29], v[48:49], v[44:45]
	s_nop 0
	v_cvt_pk_bf16_f32 v64, v44, v45
	v_pk_add_f32 v[44:45], v[50:51], 1.0 op_sel_hi:[1,0]
	s_nop 0
	v_pk_fma_f32 v[44:45], v[30:31], v[44:45], v[46:47]
	s_nop 0
	v_cvt_pk_bf16_f32 v65, v44, v45
	v_lshlrev_b64 v[44:45], 11, v[52:53]
	v_lshl_add_u64 v[52:53], v[40:41], 0, v[44:45]
	v_mov_b64_e32 v[44:45], v[68:69]
	v_mov_b64_e32 v[46:47], v[70:71]
	v_mov_b64_e32 v[48:49], v[72:73]
	v_mov_b64_e32 v[50:51], v[74:75]
	s_waitcnt vmcnt(0)
	v_pk_add_f32 v[48:49], v[48:49], 1.0 op_sel_hi:[1,0]
	s_nop 0
	v_pk_fma_f32 v[44:45], v[24:25], v[48:49], v[44:45]
	s_nop 0
	v_cvt_pk_bf16_f32 v56, v44, v45
	v_pk_add_f32 v[44:45], v[50:51], 1.0 op_sel_hi:[1,0]
	s_nop 0
	v_pk_fma_f32 v[44:45], v[26:27], v[44:45], v[46:47]
	s_nop 0
	v_cvt_pk_bf16_f32 v57, v44, v45
	v_mov_b64_e32 v[44:45], v[76:77]
	v_mov_b64_e32 v[46:47], v[78:79]
	v_mov_b64_e32 v[48:49], v[80:81]
	v_mov_b64_e32 v[50:51], v[82:83]
	s_waitcnt vmcnt(0)
	v_pk_add_f32 v[48:49], v[48:49], 1.0 op_sel_hi:[1,0]
	s_nop 0
	v_pk_fma_f32 v[44:45], v[20:21], v[48:49], v[44:45]
	s_nop 0
	v_cvt_pk_bf16_f32 v58, v44, v45
	v_pk_add_f32 v[44:45], v[50:51], 1.0 op_sel_hi:[1,0]
	s_nop 0
	v_pk_fma_f32 v[44:45], v[22:23], v[44:45], v[46:47]
	s_nop 0
	v_cvt_pk_bf16_f32 v59, v44, v45
	v_mov_b64_e32 v[44:45], v[84:85]
	v_mov_b64_e32 v[46:47], v[86:87]
	v_mov_b64_e32 v[48:49], v[88:89]
	v_mov_b64_e32 v[50:51], v[90:91]
	s_nop 0
	global_store_dwordx2 v[52:53], v[64:65], off
	global_store_dwordx2 v[52:53], v[56:57], off offset:512
	global_store_dwordx2 v[52:53], v[58:59], off offset:1024
	v_mov_b64_e32 v[30:31], v[14:15]
	v_mov_b64_e32 v[26:27], v[10:11]
	v_mov_b64_e32 v[22:23], v[6:7]
	v_mov_b64_e32 v[28:29], v[12:13]
	v_mov_b64_e32 v[24:25], v[8:9]
	v_mov_b64_e32 v[20:21], v[4:5]
	s_waitcnt vmcnt(3)
	v_pk_add_f32 v[48:49], v[48:49], 1.0 op_sel_hi:[1,0]
	s_nop 0
	v_pk_fma_f32 v[44:45], v[16:17], v[48:49], v[44:45]
	v_pk_add_f32 v[16:17], v[50:51], 1.0 op_sel_hi:[1,0]
	v_cvt_pk_bf16_f32 v44, v44, v45
	v_pk_fma_f32 v[16:17], v[18:19], v[16:17], v[46:47]
	s_nop 0
	v_cvt_pk_bf16_f32 v45, v16, v17
	v_mov_b64_e32 v[18:19], v[2:3]
	v_mov_b64_e32 v[16:17], v[0:1]
	global_store_dwordx2 v[52:53], v[44:45], off offset:1536
	s_cbranch_vccnz .LBB0_37

.LBB0_119:
	v_readlane_b32 s5, v241, 20
	v_readlane_b32 s6, v238, 23
	v_readlane_b32 s8, v243, 5
	v_add_u32_e32 v60, s5, v68
	v_add_u32_e32 v32, 0xfffff000, v60
	v_lshrrev_b32_e32 v32, 10, v32
	s_movk_i32 s5, 0xfff
	v_add_u32_e32 v32, 1, v32
	v_cmp_lt_i32_e32 vcc, s5, v60
	s_mul_i32 s5, s6, 3
	v_readlane_b32 s14, v243, 11
	v_cndmask_b32_e32 v32, 0, v32, vcc
	v_readlane_b32 s15, v243, 12
	v_readlane_b32 s7, v238, 24
	v_add_u32_e32 v34, s5, v32
	v_mov_b64_e32 v[32:33], s[14:15]
	v_mad_i64_i32 v[32:33], s[6:7], v34, s33, v[32:33]
	s_mov_b64 s[6:7], 0x3000
	s_nop 0
	v_lshl_add_u64 v[52:53], v[32:33], 0, s[6:7]
	s_mov_b64 s[6:7], 0x4000
	v_lshl_add_u64 v[54:55], v[32:33], 0, s[6:7]
	v_mov_b32_e32 v41, v129
	v_mov_b32_e32 v43, v129
	v_mov_b32_e32 v45, v129
	v_lshl_add_u64 v[66:67], v[52:53], 0, v[128:129]
	v_lshl_add_u64 v[64:65], v[54:55], 0, v[128:129]
	v_lshl_add_u64 v[62:63], v[52:53], 0, v[40:41]
	v_lshl_add_u64 v[58:59], v[54:55], 0, v[40:41]
	v_lshl_add_u64 v[56:57], v[52:53], 0, v[42:43]
	v_lshl_add_u64 v[34:35], v[54:55], 0, v[42:43]
	v_lshl_add_u64 v[32:33], v[52:53], 0, v[44:45]
	v_lshl_add_u64 v[52:53], v[54:55], 0, v[44:45]
	v_mov_b32_e32 v54, v16
	v_mov_b32_e32 v55, v20
	v_mov_b32_e32 v72, v17
	v_mov_b32_e32 v73, v21
	v_pk_add_f32 v[54:55], v[54:55], v[72:73]
	v_mov_b32_e32 v72, v18
	v_mov_b32_e32 v73, v22
	v_pk_add_f32 v[54:55], v[72:73], v[54:55]
	v_mov_b32_e32 v72, v19
	v_mov_b32_e32 v73, v23
	v_pk_add_f32 v[54:55], v[72:73], v[54:55]
	v_mov_b32_e32 v72, v25
	v_add_f32_e32 v41, 0, v54
	v_add_f32_e32 v41, v41, v55
	v_mov_b32_e32 v54, v24
	v_mov_b32_e32 v55, v28
	v_mov_b32_e32 v73, v29
	v_pk_add_f32 v[54:55], v[54:55], v[72:73]
	v_mov_b32_e32 v72, v26
	v_mov_b32_e32 v73, v30
	v_pk_add_f32 v[54:55], v[72:73], v[54:55]
	v_mov_b32_e32 v72, v27
	v_mov_b32_e32 v73, v31
	v_pk_add_f32 v[54:55], v[72:73], v[54:55]
	global_load_dwordx4 v[116:119], v[66:67], off
	global_load_dwordx4 v[120:123], v[64:65], off
	global_load_dwordx4 v[124:127], v[62:63], off
	global_load_dwordx4 v[134:137], v[58:59], off
	global_load_dwordx4 v[138:141], v[56:57], off
	global_load_dwordx4 v[146:149], v[34:35], off
	global_load_dwordx4 v[150:153], v[32:33], off
	global_load_dwordx4 v[154:157], v[52:53], off
	global_load_dwordx4 v[72:75], v[48:49], off offset:3072
	global_load_dwordx4 v[76:79], v[46:47], off offset:3072
	v_add_f32_e32 v41, v41, v54
	v_add_f32_e32 v41, v41, v55
	global_load_dwordx4 v[80:83], v[48:49], off offset:2048
	global_load_dwordx4 v[84:87], v[46:47], off offset:2048
	v_add_f32_dpp v41, v41, v41 quad_perm:[1,0,3,2] row_mask:0xf bank_mask:0xf bound_ctrl:1
	s_mov_b32 s5, 0x800000
	v_ashrrev_i32_e32 v61, 31, v60
	v_add_f32_dpp v41, v41, v41 quad_perm:[2,3,0,1] row_mask:0xf bank_mask:0xf bound_ctrl:1
	v_readlane_b32 s9, v243, 6
	v_readlane_b32 s10, v243, 7
	v_add_f32_dpp v41, v41, v41 row_half_mirror row_mask:0xf bank_mask:0xf bound_ctrl:1
	v_readlane_b32 s11, v243, 8
	v_readlane_b32 s12, v243, 9
	v_add_f32_dpp v41, v41, v41 row_mirror row_mask:0xf bank_mask:0xf bound_ctrl:1
	ds_bpermute_b32 v43, v69, v41
	v_readlane_b32 s13, v243, 10
	v_readlane_b32 s16, v243, 13
	v_readlane_b32 s17, v243, 14
	v_readlane_b32 s18, v243, 15
	s_waitcnt lgkmcnt(0)
	v_add_f32_e32 v41, v41, v43
	ds_bpermute_b32 v43, v70, v41
	v_readlane_b32 s19, v243, 16
	v_readlane_b32 s20, v243, 17
	v_readlane_b32 s21, v243, 18
	v_readlane_b32 s22, v243, 19
	s_waitcnt lgkmcnt(0)
	v_add_f32_e32 v41, v41, v43
	v_mul_f32_e32 v54, 0x3a800000, v41
	v_mov_b32_e32 v112, v54
	v_pk_add_f32 v[92:93], v[28:29], v[54:55] op_sel_hi:[1,0] neg_lo:[0,1] neg_hi:[0,1]
	v_pk_add_f32 v[96:97], v[24:25], v[54:55] op_sel_hi:[1,0] neg_lo:[0,1] neg_hi:[0,1]
	v_pk_add_f32 v[98:99], v[26:27], v[54:55] op_sel_hi:[1,0] neg_lo:[0,1] neg_hi:[0,1]
	v_mov_b32_e32 v26, v93
	v_mov_b32_e32 v27, v97
	v_pk_add_f32 v[94:95], v[30:31], v[54:55] op_sel_hi:[1,0] neg_lo:[0,1] neg_hi:[0,1]
	v_mov_b32_e32 v24, v92
	v_mov_b32_e32 v25, v96
	v_pk_mul_f32 v[26:27], v[26:27], v[26:27]
	v_mov_b32_e32 v28, v95
	v_pk_fma_f32 v[24:25], v[24:25], v[24:25], v[26:27]
	v_mov_b32_e32 v26, v94
	v_mov_b32_e32 v27, v98
	v_mov_b32_e32 v29, v99
	v_pk_fma_f32 v[24:25], v[26:27], v[26:27], v[24:25]
	v_pk_add_f32 v[102:103], v[20:21], v[54:55] op_sel_hi:[1,0] neg_lo:[0,1] neg_hi:[0,1]
	v_pk_fma_f32 v[100:101], v[28:29], v[28:29], v[24:25]
	global_load_dwordx4 v[24:27], v[48:49], off offset:1024
	global_load_dwordx4 v[88:91], v[46:47], off offset:1024
	v_pk_add_f32 v[104:105], v[22:23], v[54:55] op_sel_hi:[1,0] neg_lo:[0,1] neg_hi:[0,1]
	global_load_dwordx4 v[20:23], v[48:49], off
	global_load_dwordx4 v[28:31], v[46:47], off
	v_pk_add_f32 v[16:17], v[16:17], v[54:55] op_sel_hi:[1,0] neg_lo:[0,1] neg_hi:[0,1]
	v_mov_b32_e32 v107, v103
	v_mov_b32_e32 v106, v17
	v_pk_add_f32 v[18:19], v[18:19], v[54:55] op_sel_hi:[1,0] neg_lo:[0,1] neg_hi:[0,1]
	v_mov_b32_e32 v54, v16
	v_mov_b32_e32 v55, v102
	v_pk_mul_f32 v[106:107], v[106:107], v[106:107]
	v_mov_b32_e32 v108, v19
	v_pk_fma_f32 v[54:55], v[54:55], v[54:55], v[106:107]
	v_mov_b32_e32 v106, v18
	v_mov_b32_e32 v107, v104
	v_mov_b32_e32 v109, v105
	v_pk_fma_f32 v[54:55], v[106:107], v[106:107], v[54:55]
	v_readlane_b32 s23, v243, 20
	v_pk_fma_f32 v[54:55], v[108:109], v[108:109], v[54:55]
	s_nop 0
	v_add_f32_e32 v41, v54, v55
	v_add_f32_e32 v41, v101, v41
	v_add_f32_e32 v41, v100, v41
	s_nop 1
	v_add_f32_dpp v41, v41, v41 quad_perm:[1,0,3,2] row_mask:0xf bank_mask:0xf bound_ctrl:1
	s_nop 1
	v_add_f32_dpp v41, v41, v41 quad_perm:[2,3,0,1] row_mask:0xf bank_mask:0xf bound_ctrl:1
	s_nop 1
	v_add_f32_dpp v41, v41, v41 row_half_mirror row_mask:0xf bank_mask:0xf bound_ctrl:1
	s_nop 1
	v_add_f32_dpp v41, v41, v41 row_mirror row_mask:0xf bank_mask:0xf bound_ctrl:1
	ds_bpermute_b32 v43, v69, v41
	s_waitcnt lgkmcnt(0)
	v_add_f32_e32 v41, v41, v43
	ds_bpermute_b32 v43, v70, v41
	s_waitcnt lgkmcnt(0)
	v_add_f32_e32 v41, v41, v43
	v_fmamk_f32 v41, v41, 0x3a800000, v177
	v_cmp_gt_f32_e32 vcc, s5, v41
	v_mul_f32_e32 v43, 0x4b800000, v41
	v_readlane_b32 s5, v240, 54
	v_cndmask_b32_e32 v41, v41, v43, vcc
	v_rsq_f32_e32 v41, v41
	v_add_u32_e32 v68, s5, v68
	v_mul_f32_e32 v43, 0x45800000, v41
	v_cndmask_b32_e32 v54, v41, v43, vcc
	v_mov_b32_e32 v113, v54
	v_pk_mul_f32 v[16:17], v[16:17], v[54:55] op_sel_hi:[1,0]
	s_and_b64 vcc, exec, s[0:1]
	s_waitcnt vmcnt(0)
	v_pk_fma_f32 v[28:29], v[20:21], v[16:17], v[28:29]
	v_pk_mul_f32 v[16:17], v[18:19], v[54:55] op_sel_hi:[1,0]
	v_pk_mul_f32 v[18:19], v[94:95], v[54:55] op_sel_hi:[1,0]
	v_pk_fma_f32 v[30:31], v[22:23], v[16:17], v[30:31]
	v_pk_mul_f32 v[16:17], v[102:103], v[54:55] op_sel_hi:[1,0]
	v_pk_fma_f32 v[18:19], v[74:75], v[18:19], v[78:79]
	v_pk_fma_f32 v[24:25], v[24:25], v[16:17], v[88:89]
	v_pk_mul_f32 v[16:17], v[104:105], v[54:55] op_sel_hi:[1,0]
	s_nop 0
	v_pk_fma_f32 v[26:27], v[26:27], v[16:17], v[90:91]
	v_pk_mul_f32 v[16:17], v[96:97], v[54:55] op_sel_hi:[1,0]
	s_nop 0
	v_pk_fma_f32 v[20:21], v[80:81], v[16:17], v[84:85]
	v_pk_mul_f32 v[16:17], v[98:99], v[54:55] op_sel_hi:[1,0]
	s_nop 0
	v_pk_fma_f32 v[22:23], v[82:83], v[16:17], v[86:87]
	v_pk_mul_f32 v[16:17], v[92:93], v[54:55] op_sel_hi:[1,0]
	v_lshlrev_b64 v[114:115], 3, v[60:61]
	v_lshlrev_b64 v[54:55], 12, v[60:61]
	v_lshl_add_u64 v[114:115], v[38:39], 0, v[114:115]
	v_pk_fma_f32 v[16:17], v[72:73], v[16:17], v[76:77]
	v_mov_b64_e32 v[72:73], v[116:117]
	v_mov_b64_e32 v[74:75], v[118:119]
	s_nop 0
	v_mov_b64_e32 v[64:65], v[120:121]
	v_mov_b64_e32 v[66:67], v[122:123]
	v_lshl_add_u64 v[54:55], v[38:39], 0, v[54:55]
	v_lshlrev_b64 v[60:61], 11, v[60:61]
	v_lshl_add_u64 v[60:61], v[50:51], 0, v[60:61]
	s_waitcnt vmcnt(0)
	v_pk_add_f32 v[64:65], v[64:65], 1.0 op_sel_hi:[1,0]
	v_pk_add_f32 v[66:67], v[66:67], 1.0 op_sel_hi:[1,0]
	v_pk_fma_f32 v[64:65], v[64:65], v[28:29], v[72:73]
	v_pk_fma_f32 v[66:67], v[66:67], v[30:31], v[74:75]
	v_mov_b64_e32 v[72:73], v[124:125]
	v_mov_b64_e32 v[74:75], v[126:127]
	v_mov_b64_e32 v[76:77], v[134:135]
	v_mov_b64_e32 v[78:79], v[136:137]
	v_cvt_pk_bf16_f32 v64, v64, v65
	v_cvt_pk_bf16_f32 v65, v66, v67
	s_waitcnt vmcnt(0)
	v_pk_add_f32 v[58:59], v[76:77], 1.0 op_sel_hi:[1,0]
	v_pk_add_f32 v[62:63], v[78:79], 1.0 op_sel_hi:[1,0]
	v_pk_fma_f32 v[58:59], v[58:59], v[24:25], v[72:73]
	v_pk_fma_f32 v[62:63], v[62:63], v[26:27], v[74:75]
	v_mov_b64_e32 v[72:73], v[138:139]
	v_mov_b64_e32 v[74:75], v[140:141]
	v_mov_b64_e32 v[76:77], v[146:147]
	v_mov_b64_e32 v[78:79], v[148:149]
	v_cvt_pk_bf16_f32 v58, v58, v59
	v_cvt_pk_bf16_f32 v59, v62, v63
	s_waitcnt vmcnt(0)
	v_pk_add_f32 v[34:35], v[76:77], 1.0 op_sel_hi:[1,0]
	s_nop 0
	v_pk_fma_f32 v[34:35], v[34:35], v[20:21], v[72:73]
	s_nop 0
	v_cvt_pk_bf16_f32 v56, v34, v35
	v_pk_add_f32 v[34:35], v[78:79], 1.0 op_sel_hi:[1,0]
	s_nop 0
	v_pk_fma_f32 v[34:35], v[34:35], v[22:23], v[74:75]
	s_nop 0
	v_cvt_pk_bf16_f32 v57, v34, v35
	v_mov_b64_e32 v[32:33], v[150:151]
	v_mov_b64_e32 v[34:35], v[152:153]
	s_nop 0
	v_mov_b64_e32 v[72:73], v[154:155]
	v_mov_b64_e32 v[74:75], v[156:157]
	s_nop 0
	s_mov_b64 s[98:99], exec
	s_mov_b64 exec, 1
	global_store_dwordx2 v[114:115], v[112:113], off
	s_mov_b64 exec, s[98:99]
	global_store_dwordx2 v[60:61], v[64:65], off
	global_store_dwordx2 v[60:61], v[58:59], off offset:512
	global_store_dwordx2 v[60:61], v[56:57], off offset:1024
	v_mov_b64_e32 v[22:23], v[10:11]
	v_mov_b64_e32 v[26:27], v[6:7]
	v_mov_b64_e32 v[30:31], v[2:3]
	v_mov_b64_e32 v[20:21], v[8:9]
	v_mov_b64_e32 v[24:25], v[4:5]
	v_mov_b64_e32 v[28:29], v[0:1]
	s_waitcnt vmcnt(4)
	v_pk_add_f32 v[52:53], v[72:73], 1.0 op_sel_hi:[1,0]
	s_nop 0
	v_pk_fma_f32 v[32:33], v[52:53], v[16:17], v[32:33]
	v_pk_add_f32 v[16:17], v[74:75], 1.0 op_sel_hi:[1,0]
	v_cvt_pk_bf16_f32 v32, v32, v33
	v_pk_fma_f32 v[16:17], v[16:17], v[18:19], v[34:35]
	s_nop 0
	v_cvt_pk_bf16_f32 v33, v16, v17
	v_mov_b64_e32 v[18:19], v[14:15]
	v_mov_b64_e32 v[16:17], v[12:13]
	global_store_dwordx2 v[60:61], v[32:33], off offset:1536
	s_cbranch_vccnz .LBB0_122
